# attention loop DMA with running source pointers: V tile issued behind the opening K-fragment reads, K tile at the old mid-half-step spot (8 instructions instead of ~18, no address arithmetic)
# speedup vs baseline: 1.0059x; 1.0059x over previous
; __device__ __forceinline__ void finishSM(f32x16& p0, f32x16& p1, float alpha, float& l_reg, bf16x8& pa0, bf16x8& pa1, bf16x8& pa2, bf16x8& pa3) {
;     for (int r = 0; r < 16; ++r) p1[r] = __builtin_amdgcn_exp2f(p1[r]);
;     float ps = 0; for (int r = 0; r < 16; ++r) ps += p0[r]; for (int r = 0; r < 16; ++r) ps += p1[r];
;     { auto rr = __builtin_amdgcn_permlane32_swap(__float_as_uint(ps), __float_as_uint(ps), false, false);
;       ps = __uint_as_float(rr[0]) + __uint_as_float(rr[1]); }
;     l_reg = l_reg * alpha + ps;
;     ...
;     PK4(p0, 0, pa0); PK4(p0, 8, pa1); PK4(p1, 0, pa2); PK4(p1, 8, pa3);
;     ...
; }
; template <int KB>
; __device__ __forceinline__ void qkt(f32x16& p0, f32x16& p1, const char* K_lds, int r32, int hi, const bf16x8* qr) {
;     p0 = f32x16{}; p1 = f32x16{};
;     const char* kb[4];
; #pragma unroll
;     for (int dd = 0; dd < 4; ++dd) kb[dd] = K_lds + KB * SHM_K + KSWZ(r32, (dd * 16 + hi * 8) * 2);
; #pragma unroll
;     for (int d0 = 0; d0 < 8; ++d0) { const char* a = kb[d0 & 3] + (d0 >> 2) * 128;
;         bf16x8 b0 = *reinterpret_cast<const bf16x8*>(a);
;         bf16x8 b1 = *reinterpret_cast<const bf16x8*>(a + 32 * 256);
;         p0 = __builtin_amdgcn_mfma_f32_32x32x16_bf16(b0, qr[d0], p0, 0, 0, 0);
;         p1 = __builtin_amdgcn_mfma_f32_32x32x16_bf16(b1, qr[d0], p1, 0, 0, 0); }
; }
; template <int VB>
; __device__ __forceinline__ void pv_tile(f32x16* o, int vb0, bf16x8 pa0, bf16x8 pa1, bf16x8 pa2, bf16x8 pa3) {
;     ...
;     PV_D0(0); PV_D0(1); PV_D0(2); PV_D0(3);
.Lmy_hs1_nov:
	s_mov_b32 s100, 0
	v_add_f32_e32 v148, 0, v231
	v_add_f32_e32 v148, v233, v148
	v_add_f32_e32 v148, v229, v148
	v_add_f32_e32 v148, v232, v148
	v_add_f32_e32 v148, v228, v148
	v_add_f32_e32 v148, v230, v148
	v_add_f32_e32 v148, v226, v148
	v_add_f32_e32 v148, v227, v148
	v_add_f32_e32 v148, v223, v148
	v_add_f32_e32 v148, v225, v148
	v_add_f32_e32 v148, v209, v148
	v_add_f32_e32 v148, v224, v148
	v_add_f32_e32 v148, v206, v148
	v_add_f32_e32 v148, v208, v148
	v_add_f32_e32 v148, v205, v148
	v_add_f32_e32 v148, v207, v148
	v_exp_f32_e32 v140, v152
	v_exp_f32_e32 v141, v153
	v_exp_f32_e32 v142, v180
	v_exp_f32_e32 v143, v181
	s_waitcnt lgkmcnt(3)
	v_mfma_f32_32x32x16_bf16 v[82:97], v[66:69], v[132:135], 0
	v_exp_f32_e32 v144, v160
	v_exp_f32_e32 v145, v161
	v_exp_f32_e32 v146, v154
	v_exp_f32_e32 v147, v155
	s_waitcnt lgkmcnt(2)
	v_mfma_f32_32x32x16_bf16 v[66:81], v[70:73], v[132:135], 0
	v_exp_f32_e32 v178, v178
	v_exp_f32_e32 v179, v179
	v_exp_f32_e32 v162, v162
	v_exp_f32_e32 v163, v163
	s_waitcnt lgkmcnt(1)
	v_mfma_f32_32x32x16_bf16 v[82:97], v[100:103], v[128:131], v[82:97]
	v_add_f32_e32 v148, v178, v148
	v_add_f32_e32 v148, v179, v148
	v_add_f32_e32 v148, v162, v148
	v_exp_f32_e32 v158, v158
	s_waitcnt lgkmcnt(0)
	v_mfma_f32_32x32x16_bf16 v[66:81], v[136:139], v[128:131], v[66:81]
	v_exp_f32_e32 v159, v159
	v_exp_f32_e32 v156, v156
	v_exp_f32_e32 v157, v157
	v_add_f32_e32 v148, v163, v148
	ds_read_b128 v[100:103], v194 offset:49152
	ds_read_b128 v[136:139], v194 offset:57344
	s_waitcnt lgkmcnt(1)
	v_mfma_f32_32x32x16_bf16 v[82:97], v[100:103], v[124:127], v[82:97]
	v_add_f32_e32 v148, v158, v148
	v_add_f32_e32 v148, v159, v148
	v_add_f32_e32 v148, v156, v148
	v_add_f32_e32 v148, v157, v148
	s_waitcnt lgkmcnt(0)
	v_mfma_f32_32x32x16_bf16 v[66:81], v[136:139], v[124:127], v[66:81]
	v_add_f32_e32 v148, v140, v148
	v_add_f32_e32 v148, v141, v148
	v_add_f32_e32 v148, v142, v148
	v_add_f32_e32 v148, v143, v148
	ds_read_b128 v[100:103], v195 offset:49152
	ds_read_b128 v[136:139], v195 offset:57344
	s_waitcnt lgkmcnt(1)
	v_mfma_f32_32x32x16_bf16 v[82:97], v[100:103], v[120:123], v[82:97]
	v_add_f32_e32 v148, v144, v148
	v_add_f32_e32 v148, v145, v148
	v_add_f32_e32 v148, v146, v148
	v_add_f32_e32 v199, v147, v148
	s_waitcnt lgkmcnt(0)
	v_mfma_f32_32x32x16_bf16 v[66:81], v[136:139], v[120:123], v[66:81]
	v_mov_b32_e32 v200, v199
	s_nop 1
	v_permlane32_swap_b32_e32 v199, v200
	v_cvt_pk_bf16_f32 v148, v231, v233
	v_cvt_pk_bf16_f32 v149, v229, v232
	v_cvt_pk_bf16_f32 v150, v228, v230
	ds_read_b128 v[100:103], v169 offset:49280
	ds_read_b128 v[136:139], v169 offset:57472
	s_waitcnt lgkmcnt(1)
	v_mfma_f32_32x32x16_bf16 v[82:97], v[100:103], v[116:119], v[82:97]
	v_cvt_pk_bf16_f32 v151, v226, v227
	v_cvt_pk_bf16_f32 v152, v223, v225
	v_cvt_pk_bf16_f32 v153, v209, v224
	s_waitcnt lgkmcnt(0)
	v_mfma_f32_32x32x16_bf16 v[66:81], v[136:139], v[116:119], v[66:81]
	v_cvt_pk_bf16_f32 v154, v206, v208
	v_cvt_pk_bf16_f32 v155, v205, v207
	v_cvt_pk_bf16_f32 v158, v158, v159
	ds_read_b128 v[100:103], v193 offset:49280
	ds_read_b128 v[136:139], v193 offset:57472
	s_waitcnt lgkmcnt(1)
	v_mfma_f32_32x32x16_bf16 v[82:97], v[100:103], v[112:115], v[82:97]
	v_cvt_pk_bf16_f32 v159, v156, v157
	v_cvt_pk_bf16_f32 v156, v178, v179
	v_cvt_pk_bf16_f32 v157, v162, v163
	s_waitcnt lgkmcnt(0)
	v_mfma_f32_32x32x16_bf16 v[66:81], v[136:139], v[112:115], v[66:81]
	v_cvt_pk_bf16_f32 v160, v140, v141
	v_cvt_pk_bf16_f32 v161, v142, v143
	v_cvt_pk_bf16_f32 v162, v144, v145
	ds_read_b128 v[100:103], v194 offset:49280
	ds_read_b128 v[136:139], v194 offset:57472
	s_waitcnt lgkmcnt(1)
	v_mfma_f32_32x32x16_bf16 v[82:97], v[100:103], v[108:111], v[82:97]
	v_cvt_pk_bf16_f32 v163, v146, v147
	s_nop 0
	v_permlane32_swap_b32_e32 v148, v150
	v_permlane32_swap_b32_e32 v149, v151
	s_waitcnt lgkmcnt(0)
	v_mfma_f32_32x32x16_bf16 v[66:81], v[136:139], v[108:111], v[66:81]
	v_permlane32_swap_b32_e32 v152, v154
	v_permlane32_swap_b32_e32 v153, v155
	v_permlane32_swap_b32_e32 v156, v158
	ds_read_b128 v[100:103], v195 offset:49280
	ds_read_b128 v[136:139], v195 offset:57472
	ds_read_b64_tr_b16 v[172:173], v185 offset:0
	ds_read_b64_tr_b16 v[174:175], v185 offset:0x800
	ds_read_b64_tr_b16 v[202:203], v185 offset:0x1000
	ds_read_b64_tr_b16 v[204:205], v185 offset:0x1800
	ds_read_b64_tr_b16 v[206:207], v185 offset:0x2000
	ds_read_b64_tr_b16 v[208:209], v185 offset:0x2800
	ds_read_b64_tr_b16 v[224:225], v185 offset:0x3000
	ds_read_b64_tr_b16 v[226:227], v185 offset:0x3800
	s_waitcnt lgkmcnt(9)
	v_mfma_f32_32x32x16_bf16 v[82:97], v[100:103], v[104:107], v[82:97]
	v_permlane32_swap_b32_e32 v157, v159
	v_permlane32_swap_b32_e32 v160, v162
	v_permlane32_swap_b32_e32 v161, v163
	s_waitcnt lgkmcnt(8)
	v_mfma_f32_32x32x16_bf16 v[66:81], v[136:139], v[104:107], v[66:81]
	s_mov_b32 m0, s32
	s_nop 0
	global_load_lds_dwordx4 v[244:245], off
	s_add_i32 m0, s32, 0x2000
	s_nop 0
	global_load_lds_dwordx4 v[246:247], off
	v_lshl_add_u64 v[244:245], v[244:245], 0, v[250:251]
	v_lshl_add_u64 v[246:247], v[246:247], 0, v[250:251]
	s_waitcnt lgkmcnt(0)
	s_nop 0
	v_mfma_f32_32x32x16_bf16 v[50:65], v[148:151], v[172:175], v[50:65]
	ds_read_b64_tr_b16 v[172:173], v185 offset:0x200
	ds_read_b64_tr_b16 v[174:175], v185 offset:0xa00
	v_mfma_f32_32x32x16_bf16 v[50:65], v[152:155], v[202:205], v[50:65]
	ds_read_b64_tr_b16 v[202:203], v185 offset:0x1200
	ds_read_b64_tr_b16 v[204:205], v185 offset:0x1a00
	v_mfma_f32_32x32x16_bf16 v[50:65], v[156:159], v[206:209], v[50:65]
	ds_read_b64_tr_b16 v[206:207], v185 offset:0x2200
	ds_read_b64_tr_b16 v[208:209], v185 offset:0x2a00
	v_mfma_f32_32x32x16_bf16 v[50:65], v[160:163], v[224:227], v[50:65]
	ds_read_b64_tr_b16 v[224:225], v185 offset:0x3200
	ds_read_b64_tr_b16 v[226:227], v185 offset:0x3a00
	s_waitcnt lgkmcnt(0)
; __device__ __forceinline__ void mask_tile(f32x16& p0, f32x16& p1, int dq, unsigned W) {
;     const float NEG = -__builtin_inff();
; #pragma unroll
;     for (int r = 0; r < 16; ++r) {
;         const int c = (r & 3) + 8 * (r >> 2);
;         if ((unsigned)(dq - c) >= W) p0[r] = NEG;
;         if ((unsigned)(dq - c - 32) >= W) p1[r] = NEG;
;     }
; }
; template <int VB>
; __device__ __forceinline__ void pv_tile(f32x16* o, int vb0, bf16x8 pa0, bf16x8 pa1, bf16x8 pa2, bf16x8 pa3) {
;     ...
;     PV_D0(0); PV_D0(1); PV_D0(2); PV_D0(3);
	v_mfma_f32_32x32x16_bf16 v[34:49], v[148:151], v[172:175], v[34:49]
	ds_read_b64_tr_b16 v[172:173], v185 offset:0x400
	ds_read_b64_tr_b16 v[174:175], v185 offset:0xc00
	v_mfma_f32_32x32x16_bf16 v[34:49], v[152:155], v[202:205], v[34:49]
	ds_read_b64_tr_b16 v[202:203], v185 offset:0x1400
	ds_read_b64_tr_b16 v[204:205], v185 offset:0x1c00
	v_mfma_f32_32x32x16_bf16 v[34:49], v[156:159], v[206:209], v[34:49]
	ds_read_b64_tr_b16 v[206:207], v185 offset:0x2400
	ds_read_b64_tr_b16 v[208:209], v185 offset:0x2c00
	v_mfma_f32_32x32x16_bf16 v[34:49], v[160:163], v[224:227], v[34:49]
	ds_read_b64_tr_b16 v[224:225], v185 offset:0x3400
	ds_read_b64_tr_b16 v[226:227], v185 offset:0x3c00
	s_waitcnt lgkmcnt(0)
	v_mfma_f32_32x32x16_bf16 v[18:33], v[148:151], v[172:175], v[18:33]
	ds_read_b64_tr_b16 v[172:173], v185 offset:0x600
	ds_read_b64_tr_b16 v[174:175], v185 offset:0xe00
	v_mfma_f32_32x32x16_bf16 v[18:33], v[152:155], v[202:205], v[18:33]
	ds_read_b64_tr_b16 v[202:203], v185 offset:0x1600
	ds_read_b64_tr_b16 v[204:205], v185 offset:0x1e00
	v_mfma_f32_32x32x16_bf16 v[18:33], v[156:159], v[206:209], v[18:33]
	ds_read_b64_tr_b16 v[206:207], v185 offset:0x2600
	ds_read_b64_tr_b16 v[208:209], v185 offset:0x2e00
	v_mfma_f32_32x32x16_bf16 v[18:33], v[160:163], v[224:227], v[18:33]
	ds_read_b64_tr_b16 v[224:225], v185 offset:0x3600
	ds_read_b64_tr_b16 v[226:227], v185 offset:0x3e00
	s_waitcnt lgkmcnt(0)
	v_mfma_f32_32x32x16_bf16 v[2:17], v[148:151], v[172:175], v[2:17]
	s_cmp_le_i32 s7, s6
	v_mfma_f32_32x32x16_bf16 v[2:17], v[152:155], v[202:205], v[2:17]
	v_mfma_f32_32x32x16_bf16 v[2:17], v[156:159], v[206:209], v[2:17]
	v_mfma_f32_32x32x16_bf16 v[2:17], v[160:163], v[224:227], v[2:17]
	s_cbranch_scc1 .LBB0_91
	v_add_u32_e32 v148, 0x4000007b, v197
	v_cmp_gt_u32_e32 vcc, 2.0, v148
	v_add_u32_e32 v148, 0x5b, v197
	s_nop 0
	v_cndmask_b32_e32 v82, v220, v82, vcc
	v_cmp_lt_u32_e32 vcc, s33, v148
	v_add_u32_e32 v148, 0x7a, v197
	s_nop 0
	v_cndmask_b32_e32 v66, v220, v66, vcc
	v_cmp_lt_u32_e32 vcc, s33, v148
	v_add_u32_e32 v148, 0x5a, v197
	s_nop 0
	v_cndmask_b32_e32 v83, v220, v83, vcc
	v_cmp_lt_u32_e32 vcc, s33, v148
	v_add_u32_e32 v148, 0x79, v197
	s_nop 0
	v_cndmask_b32_e32 v67, v220, v67, vcc
	v_cmp_lt_u32_e32 vcc, s33, v148
	v_add_u32_e32 v148, 0x59, v197
	s_nop 0
	v_cndmask_b32_e32 v84, v220, v84, vcc
	v_cmp_lt_u32_e32 vcc, s33, v148
	v_add_u32_e32 v148, 0x78, v197
	s_nop 0
	v_cndmask_b32_e32 v68, v220, v68, vcc
	v_cmp_lt_u32_e32 vcc, s33, v148
	v_add_u32_e32 v148, 0x58, v197
	s_nop 0
	v_cndmask_b32_e32 v85, v220, v85, vcc
	v_cmp_lt_u32_e32 vcc, s33, v148
	v_add_u32_e32 v148, 0x73, v197
	s_nop 0
	v_cndmask_b32_e32 v69, v220, v69, vcc
	v_cmp_lt_u32_e32 vcc, s33, v148
	v_add_u32_e32 v148, 0x53, v197
	s_nop 0
	v_cndmask_b32_e32 v86, v220, v86, vcc
	v_cmp_lt_u32_e32 vcc, s33, v148
	v_add_u32_e32 v148, 0x72, v197
	s_nop 0
	v_cndmask_b32_e32 v70, v220, v70, vcc
	v_cmp_lt_u32_e32 vcc, s33, v148
	v_add_u32_e32 v148, 0x52, v197
	s_nop 0
	v_cndmask_b32_e32 v87, v220, v87, vcc
	v_cmp_lt_u32_e32 vcc, s33, v148
	v_add_u32_e32 v148, 0x71, v197
	s_nop 0
	v_cndmask_b32_e32 v71, v220, v71, vcc
	v_cmp_lt_u32_e32 vcc, s33, v148
	v_add_u32_e32 v148, 0x51, v197
	s_nop 0
	v_cndmask_b32_e32 v88, v220, v88, vcc
	v_cmp_lt_u32_e32 vcc, s33, v148
	v_add_u32_e32 v148, 0x70, v197
	s_nop 0
	v_cndmask_b32_e32 v72, v220, v72, vcc
	v_cmp_lt_u32_e32 vcc, s33, v148
	v_add_u32_e32 v148, 0x50, v197
	s_nop 0
	v_cndmask_b32_e32 v89, v220, v89, vcc
	v_cmp_lt_u32_e32 vcc, s33, v148
	v_add_u32_e32 v148, 0x6b, v197
	s_nop 0
	v_cndmask_b32_e32 v73, v220, v73, vcc
	v_cmp_lt_u32_e32 vcc, s33, v148
	v_add_u32_e32 v148, 0x4b, v197
	s_nop 0
	v_cndmask_b32_e32 v90, v220, v90, vcc
	v_cmp_lt_u32_e32 vcc, s33, v148
	v_add_u32_e32 v148, 0x6a, v197
	s_nop 0
	v_cndmask_b32_e32 v74, v220, v74, vcc
	v_cmp_lt_u32_e32 vcc, s33, v148
	v_add_u32_e32 v148, 0x4a, v197
	s_nop 0
	v_cndmask_b32_e32 v91, v220, v91, vcc
	v_cmp_lt_u32_e32 vcc, s33, v148
	v_add_u32_e32 v148, 0x69, v197
	s_nop 0
	v_cndmask_b32_e32 v75, v220, v75, vcc
	v_cmp_lt_u32_e32 vcc, s33, v148
	v_add_u32_e32 v148, 0x49, v197
	s_nop 0
	v_cndmask_b32_e32 v92, v220, v92, vcc
	v_cmp_lt_u32_e32 vcc, s33, v148
	v_add_u32_e32 v148, 0x68, v197
	s_nop 0
	v_cndmask_b32_e32 v76, v220, v76, vcc
	v_cmp_lt_u32_e32 vcc, s33, v148
	v_add_u32_e32 v148, 0x48, v197
	s_nop 0
	v_cndmask_b32_e32 v93, v220, v93, vcc
	v_cmp_lt_u32_e32 vcc, s33, v148
	v_add_u32_e32 v148, 0x63, v197
	s_nop 0
	v_cndmask_b32_e32 v77, v220, v77, vcc
	v_cmp_lt_u32_e32 vcc, s33, v148
	v_add_u32_e32 v148, 0x43, v197
	s_nop 0
	v_cndmask_b32_e32 v94, v220, v94, vcc
	v_cmp_lt_u32_e32 vcc, s33, v148
	v_add_u32_e32 v148, 0x62, v197
	s_nop 0
	v_cndmask_b32_e32 v78, v220, v78, vcc
	v_cmp_lt_u32_e32 vcc, s33, v148
	v_add_u32_e32 v148, 0x42, v197
	s_nop 0
	v_cndmask_b32_e32 v95, v220, v95, vcc
	v_cmp_lt_u32_e32 vcc, s33, v148
	v_add_u32_e32 v148, 0x61, v197
	s_nop 0
	v_cndmask_b32_e32 v79, v220, v79, vcc
	v_cmp_lt_u32_e32 vcc, s33, v148
	v_add_u32_e32 v148, 0x41, v197
	s_nop 0
	v_cndmask_b32_e32 v96, v220, v96, vcc
	v_cmp_lt_u32_e32 vcc, s33, v148
	v_add_u32_e32 v148, 0x60, v197
	s_nop 0
	v_cndmask_b32_e32 v80, v220, v80, vcc
	v_cmp_lt_u32_e32 vcc, s33, v148
	v_add_u32_e32 v148, 64, v197
	s_nop 0
	v_cndmask_b32_e32 v97, v220, v97, vcc
	v_cmp_lt_u32_e32 vcc, s33, v148
	s_nop 1
	v_cndmask_b32_e32 v81, v220, v81, vcc

; __device__ __forceinline__ void partialSM(f32x16& p0, f32x16& p1, float& m_reg, float& mn, float& alpha, bool rs) {
;     ...
;     if (__builtin_expect(__all((pmax - m_reg) * SCALE <= THR), 1)) { mn = m_reg; alpha = 1.f; }
;     else { mn = fmaxf(m_reg, pmax); alpha = __builtin_amdgcn_exp2f((m_reg - mn) * C2); m_reg = mn; }
;     const float mnL = rs ? -mn * C2 : -__builtin_inff();
;     for (int r = 0; r < 16; ++r) p0[r] = fmaf(p0[r], C2, mnL); for (int r = 0; r < 16; ++r) p1[r] = fmaf(p1[r], C2, mnL);
;     for (int r = 0; r < 16; ++r) p0[r] = __builtin_amdgcn_exp2f(p0[r]);
; }
.LBB0_95:
	v_cndmask_b32_e64 v179, v148, v198, s[42:43]
	v_mul_f32_e32 v148, 0xbe0293ee, v179
	v_cndmask_b32_e64 v180, v220, v148, s[40:41]
	v_fmamk_f32 v82, v82, 0x3e0293ee, v180
	v_fmamk_f32 v83, v83, 0x3e0293ee, v180
	v_fmamk_f32 v84, v84, 0x3e0293ee, v180
	v_fmamk_f32 v85, v85, 0x3e0293ee, v180
	v_fmamk_f32 v86, v86, 0x3e0293ee, v180
	v_fmamk_f32 v87, v87, 0x3e0293ee, v180
	v_fmamk_f32 v88, v88, 0x3e0293ee, v180
	v_fmamk_f32 v89, v89, 0x3e0293ee, v180
	v_fmamk_f32 v90, v90, 0x3e0293ee, v180
	v_fmamk_f32 v91, v91, 0x3e0293ee, v180
	v_fmamk_f32 v92, v92, 0x3e0293ee, v180
	v_fmamk_f32 v93, v93, 0x3e0293ee, v180
	v_fmamk_f32 v94, v94, 0x3e0293ee, v180
	v_fmamk_f32 v95, v95, 0x3e0293ee, v180
	v_fmamk_f32 v96, v96, 0x3e0293ee, v180
	v_fmamk_f32 v97, v97, 0x3e0293ee, v180
	v_exp_f32_e32 v148, v82
	v_exp_f32_e32 v163, v83
	v_exp_f32_e32 v149, v84
	v_exp_f32_e32 v162, v85
	v_exp_f32_e32 v150, v86
	v_exp_f32_e32 v161, v87
	v_exp_f32_e32 v151, v88
	v_exp_f32_e32 v160, v89
	v_exp_f32_e32 v152, v90
	v_exp_f32_e32 v159, v91
	v_exp_f32_e32 v153, v92
	v_exp_f32_e32 v158, v93
	v_exp_f32_e32 v154, v94
	v_exp_f32_e32 v157, v95
	v_exp_f32_e32 v155, v96
	v_exp_f32_e32 v156, v97
	v_fmamk_f32 v203, v73, 0x3e0293ee, v180
	v_fmamk_f32 v204, v74, 0x3e0293ee, v180
	v_fmamk_f32 v208, v66, 0x3e0293ee, v180
	v_fmamk_f32 v209, v67, 0x3e0293ee, v180
	v_fmamk_f32 v223, v68, 0x3e0293ee, v180
	v_fmamk_f32 v224, v69, 0x3e0293ee, v180
	v_fmamk_f32 v225, v70, 0x3e0293ee, v180
	v_fmamk_f32 v198, v71, 0x3e0293ee, v180
	v_fmamk_f32 v201, v72, 0x3e0293ee, v180
	v_fmamk_f32 v205, v75, 0x3e0293ee, v180
	v_fmamk_f32 v206, v76, 0x3e0293ee, v180
	v_fmamk_f32 v207, v77, 0x3e0293ee, v180
	v_fmamk_f32 v181, v78, 0x3e0293ee, v180
	v_fmamk_f32 v226, v79, 0x3e0293ee, v180
	v_fmamk_f32 v227, v80, 0x3e0293ee, v180
	v_fmac_f32_e32 v180, 0x3e0293ee, v81
	s_waitcnt lgkmcnt(0)
	s_barrier
; __device__ __forceinline__ void finishSM(f32x16& p0, f32x16& p1, float alpha, float& l_reg, bf16x8& pa0, bf16x8& pa1, bf16x8& pa2, bf16x8& pa3) {
;     for (int r = 0; r < 16; ++r) p1[r] = __builtin_amdgcn_exp2f(p1[r]);
;     float ps = 0; for (int r = 0; r < 16; ++r) ps += p0[r]; for (int r = 0; r < 16; ++r) ps += p1[r];
;     { auto rr = __builtin_amdgcn_permlane32_swap(__float_as_uint(ps), __float_as_uint(ps), false, false);
;       ps = __uint_as_float(rr[0]) + __uint_as_float(rr[1]); }
;     l_reg = l_reg * alpha + ps;
;     ...
;     PK4(p0, 0, pa0); PK4(p0, 8, pa1); PK4(p1, 0, pa2); PK4(p1, 8, pa3);
;     ...
; }
; template <int KB>
; __device__ __forceinline__ void qkt(f32x16& p0, f32x16& p1, const char* K_lds, int r32, int hi, const bf16x8* qr) {
;     p0 = f32x16{}; p1 = f32x16{};
;     const char* kb[4];
; #pragma unroll
;     for (int dd = 0; dd < 4; ++dd) kb[dd] = K_lds + KB * SHM_K + KSWZ(r32, (dd * 16 + hi * 8) * 2);
; #pragma unroll
;     for (int d0 = 0; d0 < 8; ++d0) { const char* a = kb[d0 & 3] + (d0 >> 2) * 128;
;         bf16x8 b0 = *reinterpret_cast<const bf16x8*>(a);
;         bf16x8 b1 = *reinterpret_cast<const bf16x8*>(a + 32 * 256);
;         p0 = __builtin_amdgcn_mfma_f32_32x32x16_bf16(b0, qr[d0], p0, 0, 0, 0);
;         p1 = __builtin_amdgcn_mfma_f32_32x32x16_bf16(b1, qr[d0], p1, 0, 0, 0); }
; }
	ds_read_b128 v[66:69], v169 offset:32768
	ds_read_b128 v[70:73], v169 offset:40960
	ds_read_b128 v[172:175], v193 offset:32768
	ds_read_b128 v[228:231], v193 offset:40960
	s_lshl_b32 m0, s32, 1
	s_sub_i32 m0, m0, 0x10000
	s_nop 0
	global_load_lds_dwordx4 v[248:249], off
	s_add_i32 m0, m0, 896
	s_nop 0
	global_load_lds_dwordx4 v[248:249], off offset:128
	v_lshl_add_u64 v[248:249], v[248:249], 0, v[250:251]
	v_exp_f32_e32 v198, v198
	v_exp_f32_e32 v201, v201
	v_exp_f32_e32 v214, v204
	v_exp_f32_e32 v205, v205
	v_exp_f32_e32 v206, v206
	v_exp_f32_e32 v207, v207
	v_exp_f32_e32 v181, v181
	v_exp_f32_e32 v215, v226
	v_exp_f32_e32 v216, v227
	v_exp_f32_e32 v180, v180
	v_exp_f32_e32 v218, v209
	v_exp_f32_e32 v209, v203
	v_add_f32_e32 v203, 0, v148
	v_add_f32_e32 v203, v163, v203
	v_add_f32_e32 v203, v149, v203
	v_add_f32_e32 v203, v162, v203
	v_add_f32_e32 v203, v150, v203
	v_add_f32_e32 v203, v161, v203
	v_add_f32_e32 v203, v151, v203
	v_add_f32_e32 v203, v160, v203
	s_waitcnt lgkmcnt(3)
	v_mfma_f32_32x32x16_bf16 v[82:97], v[66:69], v[132:135], 0
	v_add_f32_e32 v203, v152, v203
	v_add_f32_e32 v203, v159, v203
	v_add_f32_e32 v203, v153, v203
	v_add_f32_e32 v203, v158, v203
	s_waitcnt lgkmcnt(2)
	v_mfma_f32_32x32x16_bf16 v[66:81], v[70:73], v[132:135], 0
	v_exp_f32_e32 v217, v208
	v_add_f32_e32 v203, v154, v203
	v_add_f32_e32 v203, v157, v203
	v_exp_f32_e32 v219, v223
	s_waitcnt lgkmcnt(1)
	v_mfma_f32_32x32x16_bf16 v[82:97], v[172:175], v[128:131], v[82:97]
	v_add_f32_e32 v203, v155, v203
	v_exp_f32_e32 v222, v224
	v_add_f32_e32 v203, v156, v203
	v_exp_f32_e32 v208, v225
	s_waitcnt lgkmcnt(0)
	v_mfma_f32_32x32x16_bf16 v[66:81], v[228:231], v[128:131], v[66:81]
	v_add_f32_e32 v203, v217, v203
	v_add_f32_e32 v203, v218, v203
	v_add_f32_e32 v203, v219, v203
	v_add_f32_e32 v203, v222, v203
	ds_read_b128 v[172:175], v194 offset:32768
	ds_read_b128 v[228:231], v194 offset:40960
	s_waitcnt lgkmcnt(1)
	v_mfma_f32_32x32x16_bf16 v[82:97], v[172:175], v[124:127], v[82:97]
	v_add_f32_e32 v203, v208, v203
	v_add_f32_e32 v203, v198, v203
	v_add_f32_e32 v203, v201, v203
	v_add_f32_e32 v203, v209, v203
	s_waitcnt lgkmcnt(0)
	v_mfma_f32_32x32x16_bf16 v[66:81], v[228:231], v[124:127], v[66:81]
	v_add_f32_e32 v203, v214, v203
	v_add_f32_e32 v203, v205, v203
	v_add_f32_e32 v203, v206, v203
	v_add_f32_e32 v203, v207, v203
	ds_read_b128 v[172:175], v195 offset:32768
	ds_read_b128 v[228:231], v195 offset:40960
	s_waitcnt lgkmcnt(1)
	v_mfma_f32_32x32x16_bf16 v[82:97], v[172:175], v[120:123], v[82:97]
	v_add_f32_e32 v203, v181, v203
	v_add_f32_e32 v203, v215, v203
	v_add_f32_e32 v203, v216, v203
	v_add_f32_e32 v203, v180, v203
	s_waitcnt lgkmcnt(0)
	v_mfma_f32_32x32x16_bf16 v[66:81], v[228:231], v[120:123], v[66:81]
	v_mov_b32_e32 v204, v203
	v_cvt_pk_bf16_f32 v148, v148, v163
	v_cvt_pk_bf16_f32 v149, v149, v162
	v_cvt_pk_bf16_f32 v150, v150, v161
	ds_read_b128 v[172:175], v169 offset:32896
	ds_read_b128 v[228:231], v169 offset:41088
	s_waitcnt lgkmcnt(1)
	v_mfma_f32_32x32x16_bf16 v[82:97], v[172:175], v[116:119], v[82:97]
	v_cvt_pk_bf16_f32 v151, v151, v160
	v_cvt_pk_bf16_f32 v152, v152, v159
	v_cvt_pk_bf16_f32 v153, v153, v158
	v_cvt_pk_bf16_f32 v154, v154, v157
	s_waitcnt lgkmcnt(0)
	v_mfma_f32_32x32x16_bf16 v[66:81], v[228:231], v[116:119], v[66:81]
	v_cvt_pk_bf16_f32 v155, v155, v156
	v_cvt_pk_bf16_f32 v156, v217, v218
	v_cvt_pk_bf16_f32 v157, v219, v222
	ds_read_b128 v[172:175], v193 offset:32896
	ds_read_b128 v[228:231], v193 offset:41088
	s_waitcnt lgkmcnt(1)
	v_mfma_f32_32x32x16_bf16 v[82:97], v[172:175], v[112:115], v[82:97]
	v_cvt_pk_bf16_f32 v158, v208, v198
	v_cvt_pk_bf16_f32 v159, v201, v209
	v_cvt_pk_bf16_f32 v160, v214, v205
	s_waitcnt lgkmcnt(0)
	v_mfma_f32_32x32x16_bf16 v[66:81], v[228:231], v[112:115], v[66:81]
	v_cvt_pk_bf16_f32 v161, v206, v207
	v_cvt_pk_bf16_f32 v162, v181, v215
	v_cvt_pk_bf16_f32 v163, v216, v180
	ds_read_b128 v[172:175], v194 offset:32896
	ds_read_b128 v[228:231], v194 offset:41088
	s_waitcnt lgkmcnt(1)
	v_mfma_f32_32x32x16_bf16 v[82:97], v[172:175], v[108:111], v[82:97]
	s_nop 1
	v_permlane32_swap_b32_e32 v203, v204
	v_permlane32_swap_b32_e32 v148, v150
	v_permlane32_swap_b32_e32 v149, v151
	s_waitcnt lgkmcnt(0)
	v_mfma_f32_32x32x16_bf16 v[66:81], v[228:231], v[108:111], v[66:81]
	v_permlane32_swap_b32_e32 v152, v154
	v_permlane32_swap_b32_e32 v153, v155
	v_permlane32_swap_b32_e32 v156, v158
	ds_read_b128 v[172:175], v195 offset:32896
	ds_read_b128 v[228:231], v195 offset:41088
	ds_read_b64_tr_b16 v[206:207], v185 offset:0x5000
	ds_read_b64_tr_b16 v[208:209], v185 offset:0x5800
	ds_read_b64_tr_b16 v[224:225], v185 offset:0x6000
	ds_read_b64_tr_b16 v[226:227], v185 offset:0x6800
	s_waitcnt lgkmcnt(5)
	v_mfma_f32_32x32x16_bf16 v[82:97], v[172:175], v[104:107], v[82:97]
	v_permlane32_swap_b32_e32 v157, v159
	v_permlane32_swap_b32_e32 v160, v162
	v_permlane32_swap_b32_e32 v161, v163
	s_waitcnt lgkmcnt(4)
	v_mfma_f32_32x32x16_bf16 v[66:81], v[228:231], v[104:107], v[66:81]
	ds_read_b64_tr_b16 v[172:173], v185 offset:0x4000
	ds_read_b64_tr_b16 v[174:175], v185 offset:0x4800
	ds_read_b64_tr_b16 v[228:229], v185 offset:0x7000
	ds_read_b64_tr_b16 v[230:231], v185 offset:0x7800
	s_cmp_lt_u32 s3, s2
	s_cselect_b64 s[22:23], -1, 0
	s_cmp_ge_u32 s3, s2
	s_cbranch_scc1 .LBB0_97
	s_add_i32 m0, s32, 0x4000
	s_nop 0
	global_load_lds_dwordx4 v[244:245], off
	s_add_i32 m0, s32, 0x6000
	s_nop 0
	global_load_lds_dwordx4 v[246:247], off
	v_lshl_add_u64 v[244:245], v[244:245], 0, v[250:251]
	v_lshl_add_u64 v[246:247], v[246:247], 0, v[250:251]
	s_mov_b32 s100, 1
